# GLA scan: static priority 2 for the state/output waves (waves 0-3), loaders stay at 0
# baseline (speedup 1.0000x reference)
.Lsc_osetup:
	s_lshr_b32 s14, s0, 2
	s_mul_i32 s14, s14, 0x1a00000
	s_add_u32 s42, s96, s14
	s_addc_u32 s43, s97, 0
	s_movk_i32 s14, 0x110
	s_lshl_b32 s50, s7, 4
	v_add_u32_e32 v88, s50, v92
	v_mul_u32_u24_e32 v88, s14, v88
	v_lshl_add_u32 v88, v93, 4, v88
	v_add_u32_e32 v90, s50, v92
	v_mul_u32_u24_e32 v90, s45, v90
	s_and_b32 s50, s0, 3
	s_lshl_b32 s50, s50, 9
	s_lshl_b32 s51, s1, 6
	s_add_i32 s50, s50, s51
	v_lshl_add_u32 v90, v93, 4, v90
	v_add_u32_e32 v90, s50, v90
	v_lshrrev_b32_e32 v94, 2, v92
	v_and_b32_e32 v95, 3, v92
	v_lshl_add_u32 v94, v94, 3, v95
	v_mul_u32_u24_e32 v89, s14, v94
	v_lshl_add_u32 v89, v93, 4, v89
	v_add_u32_e32 v89, 91136, v89
	v_lshrrev_b32_e32 v95, 4, v94
	v_lshl_add_u32 v89, v95, 6, v89
	s_barrier
	s_setprio 2

.Lsc_oepi:
	s_setprio 0
	ds_read_b128 v[40:43], v89 offset:17408
	ds_read_b128 v[44:47], v89 offset:17472
	ds_read_b128 v[48:51], v89 offset:17536
	ds_read_b128 v[52:55], v89 offset:17600
	ds_read_b128 v[128:131], v89 offset:18496
	ds_read_b128 v[132:135], v89 offset:18560
	ds_read_b128 v[136:139], v89 offset:18624
	ds_read_b128 v[140:143], v89 offset:18688
	s_waitcnt lgkmcnt(4)
	v_mfma_f32_16x16x32_bf16 v[24:27], v[40:43], v[72:75], 0
	v_mfma_f32_16x16x32_bf16 v[24:27], v[44:47], v[76:79], v[24:27]
	v_mfma_f32_16x16x32_bf16 v[24:27], v[48:51], v[80:83], v[24:27]
	v_mfma_f32_16x16x32_bf16 v[24:27], v[52:55], v[84:87], v[24:27]
	s_waitcnt lgkmcnt(0)
	v_mfma_f32_16x16x32_bf16 v[28:31], v[128:131], v[72:75], 0
	v_mfma_f32_16x16x32_bf16 v[28:31], v[132:135], v[76:79], v[28:31]
	v_mfma_f32_16x16x32_bf16 v[28:31], v[136:139], v[80:83], v[28:31]
	v_mfma_f32_16x16x32_bf16 v[28:31], v[140:143], v[84:87], v[28:31]
	s_nop 7
	v_cvt_pk_bf16_f32 v24, v24, v25
	v_cvt_pk_bf16_f32 v25, v26, v27
	v_cvt_pk_bf16_f32 v26, v28, v29
	v_cvt_pk_bf16_f32 v27, v30, v31
	global_store_dwordx4 v90, v[24:27], s[42:43]
	s_add_u32 s42, s42, 0x68000
	s_addc_u32 s43, s43, 0
	s_branch .LBB0_176
